# epilogue-batched-loads+relu2-canonicalize-removed+dilated-unit-top-wait-removed
# speedup vs baseline: 1.0022x; 1.0022x over previous
; #define GAS __attribute__((address_space(1)))
; template <int MODE> ...
;     ...
;     if (load_bias) {
;         if (MODE == 0) {
;             float tb[8];
; #pragma unroll
;             for (int k = 0; k < 8; ++k) { const int i = tid + NT_ * k; tb[k] = *(const GAS float*)(biasT + (size_t)(2 * hp + (i >> 11)) * 2048 + (i & 2047)); }
; #pragma unroll
;             for (int k = 0; k < 8; ++k) { const int i = tid + NT_ * k; biasL[i] = tb[k]; }
;         } else {
;             for (int i = tid; i < 2 * 129; i += NT_) { const int mm = i / 129, ii = i - mm * 129; biasL[mm * 2048 + ii] = biasT[(size_t)(2 * hp + mm) * 2048 + min(ii * dil, 2047)]; }
; __global__ void __launch_bounds__(NT_, 2) fwd_mega(Args args) {
;     ...
;                     int last_hp = -1;
;                     for (int u = bid; u < 4096; u += G) { const int bh = u & 255, r = u >> 8; const int c = r % dil, jb = r / dil;
;                         attn_unit<1>(lds, QKb, VTb, biasT, bh >> 3, bh & 7, c, dil, jb, AOb, LSEb, gi, 0.f, nullptr, 0.f, (bh & 7) != last_hp); last_hp = bh & 7; }
.LBB0_427:
	s_mov_b32 s0, s25
	s_and_b32 s25, s26, 7
	s_cmp_lg_u32 s25, s0
	v_mov_b32_e32 v2, v206
	s_movk_i32 s10, 0x102
	s_cselect_b64 s[0:1], -1, 0
	s_lshl_b32 s27, s25, 1
	v_cmp_gt_i32_e32 vcc, s10, v2
	v_readfirstlane_b32 s14, v2
	s_and_b64 s[10:11], s[0:1], vcc
	s_and_saveexec_b64 s[0:1], s[10:11]
	s_cbranch_execz .LBB0_430
	s_add_i32 s10, 0, 0x11000
	v_lshl_add_u32 v0, v2, 2, s10
	s_mov_b64 s[10:11], 0
	v_mov_b32_e32 v3, v2

; __device__ __forceinline__ unsigned cvt_pk_bf16(float lo, float hi) { f32x2_t v = {lo, hi}; bf16x2_t b = __builtin_convertvector(v, bf16x2_t); return __builtin_bit_cast(unsigned, b); }
;     __device__ __forceinline__ void operator()(const f32x4 (&acc)[2][2][4][2], const Unit& u, int wr, int wc, int fr, int fq) const {
;         const int row0 = u.pm * BM + wr * 64 + fr; const int col0 = u.pn * BM + wc * 32 + 8 * fq;
; #pragma unroll
;         for (int ai = 0; ai < 2; ++ai)
; #pragma unroll
;             for (int m = 0; m < 4; ++m) { bf16* rowp = O + (size_t)(row0 + ai * HALF + m * 16) * ldc + col0;
; #pragma unroll
;                 for (int bj = 0; bj < 2; ++bj) { f32x4 v0 = acc[ai][bj][m][0], v1 = acc[ai][bj][m][1];
;                     if (ACT == 1) {
; #pragma unroll
;                         for (int e = 0; e < 4; ++e) { float a = fmaxf(v0[e], 0.f), b = fmaxf(v1[e], 0.f); v0[e] = a * a; v1[e] = b * b; } }
;                     u32x4 w; w.x = cvt_pk_bf16(v0[0], v0[1]); w.y = cvt_pk_bf16(v0[2], v0[3]); w.z = cvt_pk_bf16(v1[0], v1[1]); w.w = cvt_pk_bf16(v1[2], v1[3]);
;                     *(u32x4*)(rowp + bj * HALF) = w; } }
.LBB0_1113:
	v_mov_b32_e32 v136, v206
	s_lshl_b32 s17, s22, 8
	v_readfirstlane_b32 s15, v136
	s_ashr_i32 s22, s15, 2
	s_andn2_b32 s22, s22, 63
	s_lshr_b32 s15, s15, 1
	s_add_i32 s22, s22, s17
	s_lshl_b32 s17, s47, 8
	s_and_b32 s15, s15, 0x60
	v_and_or_b32 v140, v136, 15, s22
	s_or_b32 s15, s15, s17
	v_lshrrev_b32_e32 v136, 1, v136
	v_and_or_b32 v136, v136, 24, s15
	v_ashrrev_i32_e32 v141, 31, v140
	v_ashrrev_i32_e32 v137, 31, v136
	v_lshlrev_b64 v[142:143], 13, v[140:141]
	v_lshl_add_u64 v[142:143], s[6:7], 0, v[142:143]
	v_lshlrev_b64 v[144:145], 1, v[136:137]
	v_max_f32_e32 v122, 0, v122
	v_max_f32_e32 v123, 0, v123
	v_lshl_add_u64 v[136:137], v[142:143], 0, v[144:145]
	v_pk_mul_f32 v[142:143], v[122:123], v[122:123]
	v_max_f32_e32 v124, 0, v124
	v_max_f32_e32 v126, 0, v126
	v_max_f32_e32 v127, 0, v127
	v_max_f32_e32 v122, 0, v128
	v_max_f32_e32 v123, 0, v129
	v_max_f32_e32 v125, 0, v125
	v_pk_mul_f32 v[126:127], v[126:127], v[126:127]
	v_pk_mul_f32 v[128:129], v[122:123], v[122:123]
	v_pk_mul_f32 v[146:147], v[124:125], v[124:125]
	v_cvt_pk_bf16_f32 v122, v126, v127
	v_cvt_pk_bf16_f32 v123, v128, v129
	v_cvt_pk_bf16_f32 v124, v142, v143
	v_cvt_pk_bf16_f32 v125, v146, v147
	v_max_f32_e32 v114, 0, v114
	v_max_f32_e32 v115, 0, v115
	flat_store_dwordx4 v[136:137], v[122:125]
	s_nop 1
	v_pk_mul_f32 v[122:123], v[114:115], v[114:115]
	v_max_f32_e32 v116, 0, v116
	v_max_f32_e32 v118, 0, v118
	v_max_f32_e32 v119, 0, v119
	v_max_f32_e32 v114, 0, v120
	v_max_f32_e32 v115, 0, v121
	v_max_f32_e32 v117, 0, v117
	v_pk_mul_f32 v[118:119], v[118:119], v[118:119]
	v_pk_mul_f32 v[120:121], v[114:115], v[114:115]
	v_pk_mul_f32 v[124:125], v[116:117], v[116:117]
	v_cvt_pk_bf16_f32 v114, v118, v119
	v_cvt_pk_bf16_f32 v115, v120, v121
	v_cvt_pk_bf16_f32 v116, v122, v123
	v_cvt_pk_bf16_f32 v117, v124, v125
	v_max_f32_e32 v106, 0, v106
	v_max_f32_e32 v107, 0, v107
	flat_store_dwordx4 v[136:137], v[114:117] offset:256
	s_nop 1
	v_or_b32_e32 v114, 16, v140
	v_pk_mul_f32 v[116:117], v[106:107], v[106:107]
	v_ashrrev_i32_e32 v115, 31, v114
	v_max_f32_e32 v108, 0, v108
	v_lshlrev_b64 v[114:115], 13, v[114:115]
	v_max_f32_e32 v110, 0, v110
	v_max_f32_e32 v111, 0, v111
	v_max_f32_e32 v106, 0, v112
	v_max_f32_e32 v107, 0, v113
	v_max_f32_e32 v109, 0, v109
	v_lshl_add_u64 v[114:115], s[6:7], 0, v[114:115]
	v_pk_mul_f32 v[110:111], v[110:111], v[110:111]
	v_pk_mul_f32 v[112:113], v[106:107], v[106:107]
	v_pk_mul_f32 v[118:119], v[108:109], v[108:109]
	v_lshl_add_u64 v[114:115], v[114:115], 0, v[144:145]
	v_cvt_pk_bf16_f32 v106, v110, v111
	v_cvt_pk_bf16_f32 v107, v112, v113
	v_cvt_pk_bf16_f32 v108, v116, v117
	v_cvt_pk_bf16_f32 v109, v118, v119
	v_max_f32_e32 v98, 0, v98
	v_max_f32_e32 v99, 0, v99
	flat_store_dwordx4 v[114:115], v[106:109]
	s_nop 1
	v_pk_mul_f32 v[106:107], v[98:99], v[98:99]
	v_max_f32_e32 v100, 0, v100
	v_max_f32_e32 v102, 0, v102
	v_max_f32_e32 v103, 0, v103
	v_max_f32_e32 v98, 0, v104
	v_max_f32_e32 v99, 0, v105
	v_max_f32_e32 v101, 0, v101
	v_pk_mul_f32 v[102:103], v[102:103], v[102:103]
	v_pk_mul_f32 v[104:105], v[98:99], v[98:99]
	v_pk_mul_f32 v[108:109], v[100:101], v[100:101]
	v_cvt_pk_bf16_f32 v98, v102, v103
	v_cvt_pk_bf16_f32 v99, v104, v105
	v_cvt_pk_bf16_f32 v100, v106, v107
	v_cvt_pk_bf16_f32 v101, v108, v109
	v_max_f32_e32 v90, 0, v90
	v_max_f32_e32 v91, 0, v91
	flat_store_dwordx4 v[114:115], v[98:101] offset:256
	s_nop 1
	v_or_b32_e32 v98, 32, v140
	v_pk_mul_f32 v[100:101], v[90:91], v[90:91]
	v_ashrrev_i32_e32 v99, 31, v98
	v_max_f32_e32 v92, 0, v92
	v_lshlrev_b64 v[98:99], 13, v[98:99]
	v_max_f32_e32 v94, 0, v94
	v_max_f32_e32 v95, 0, v95
	v_max_f32_e32 v90, 0, v96
	v_max_f32_e32 v91, 0, v97
	v_max_f32_e32 v93, 0, v93
	v_lshl_add_u64 v[98:99], s[6:7], 0, v[98:99]
	v_pk_mul_f32 v[94:95], v[94:95], v[94:95]
	v_pk_mul_f32 v[96:97], v[90:91], v[90:91]
	v_pk_mul_f32 v[102:103], v[92:93], v[92:93]
	v_lshl_add_u64 v[98:99], v[98:99], 0, v[144:145]
	v_cvt_pk_bf16_f32 v90, v94, v95
	v_cvt_pk_bf16_f32 v91, v96, v97
	v_cvt_pk_bf16_f32 v92, v100, v101
	v_cvt_pk_bf16_f32 v93, v102, v103
	v_max_f32_e32 v82, 0, v82
	v_max_f32_e32 v83, 0, v83
	flat_store_dwordx4 v[98:99], v[90:93]
	s_nop 1
	v_pk_mul_f32 v[90:91], v[82:83], v[82:83]
	v_max_f32_e32 v84, 0, v84
	v_max_f32_e32 v86, 0, v86
	v_max_f32_e32 v87, 0, v87
	v_max_f32_e32 v82, 0, v88
	v_max_f32_e32 v83, 0, v89
	v_max_f32_e32 v85, 0, v85
	v_pk_mul_f32 v[86:87], v[86:87], v[86:87]
	v_pk_mul_f32 v[88:89], v[82:83], v[82:83]
	v_pk_mul_f32 v[92:93], v[84:85], v[84:85]
	v_cvt_pk_bf16_f32 v82, v86, v87
	v_cvt_pk_bf16_f32 v83, v88, v89
	v_cvt_pk_bf16_f32 v84, v90, v91
	v_cvt_pk_bf16_f32 v85, v92, v93
	v_max_f32_e32 v74, 0, v74
	v_max_f32_e32 v75, 0, v75
	flat_store_dwordx4 v[98:99], v[82:85] offset:256
	s_nop 1
	v_or_b32_e32 v82, 48, v140
	v_pk_mul_f32 v[84:85], v[74:75], v[74:75]
	v_ashrrev_i32_e32 v83, 31, v82
	v_max_f32_e32 v76, 0, v76
	v_lshlrev_b64 v[82:83], 13, v[82:83]
	v_max_f32_e32 v78, 0, v78
	v_max_f32_e32 v79, 0, v79
	v_max_f32_e32 v74, 0, v80
	v_max_f32_e32 v75, 0, v81
	v_max_f32_e32 v77, 0, v77
	v_lshl_add_u64 v[82:83], s[6:7], 0, v[82:83]
	v_pk_mul_f32 v[78:79], v[78:79], v[78:79]
	v_pk_mul_f32 v[80:81], v[74:75], v[74:75]
	v_pk_mul_f32 v[86:87], v[76:77], v[76:77]
	v_lshl_add_u64 v[82:83], v[82:83], 0, v[144:145]
	v_cvt_pk_bf16_f32 v74, v78, v79
	v_cvt_pk_bf16_f32 v75, v80, v81
	v_cvt_pk_bf16_f32 v76, v84, v85
	v_cvt_pk_bf16_f32 v77, v86, v87
	v_max_f32_e32 v66, 0, v66
	v_max_f32_e32 v67, 0, v67
	flat_store_dwordx4 v[82:83], v[74:77]
	s_nop 1
	v_pk_mul_f32 v[74:75], v[66:67], v[66:67]
	v_max_f32_e32 v68, 0, v68
	v_max_f32_e32 v70, 0, v70
	v_max_f32_e32 v71, 0, v71
	v_max_f32_e32 v66, 0, v72
; __device__ __forceinline__ int opaque_tid() { int t = threadIdx.x; asm volatile("" : "+v"(t)); return t; }
; __device__ __forceinline__ unsigned cvt_pk_bf16(float lo, float hi) { f32x2_t v = {lo, hi}; bf16x2_t b = __builtin_convertvector(v, bf16x2_t); return __builtin_bit_cast(unsigned, b); }
; #define PG8_BAR __builtin_amdgcn_s_barrier()
;     __device__ __forceinline__ void operator()(const f32x4 (&acc)[2][2][4][2], const Unit& u, int wr, int wc, int fr, int fq) const {
;     ...
;             for (int m = 0; m < 4; ++m) { bf16* rowp = O + (size_t)(row0 + ai * HALF + m * 16) * ldc + col0;
; #pragma unroll
;                 for (int bj = 0; bj < 2; ++bj) { f32x4 v0 = acc[ai][bj][m][0], v1 = acc[ai][bj][m][1];
;                     if (ACT == 1) {
; #pragma unroll
;                         for (int e = 0; e < 4; ++e) { float a = fmaxf(v0[e], 0.f), b = fmaxf(v1[e], 0.f); v0[e] = a * a; v1[e] = b * b; } }
;                     u32x4 w; w.x = cvt_pk_bf16(v0[0], v0[1]); w.y = cvt_pk_bf16(v0[2], v0[3]); w.z = cvt_pk_bf16(v1[0], v1[1]); w.w = cvt_pk_bf16(v1[2], v1[3]);
;                     *(u32x4*)(rowp + bj * HALF) = w; } }
; template <class Epi, class Sched>
; __device__ __forceinline__ void gemm_phase(LAS unsigned char* lds, Gemm g, Sched S, const Epi& E) {
;     ...
;         if (wr == 0) PG8_BAR;
;         { const int te = opaque_tid(), we = __builtin_amdgcn_readfirstlane(te >> 6), le = te & 63;
;           E(acc, cur, we >> 2, we & 3, le & 15, le >> 4); }
;         if (!has_next) break;
; #pragma unroll
;         for (int a = 0; a < 2; ++a)
; #pragma unroll
;             for (int b = 0; b < 2; ++b)
; #pragma unroll
;                 for (int m = 0; m < 4; ++m)
; #pragma unroll
;                     for (int n = 0; n < 2; ++n) acc[a][b][m][n] = (f32x4){0.f, 0.f, 0.f, 0.f};
;         cur = nxt; cA = nA; cB = nB; ++ui;
;         if (wr == 1) PG8_BAR;
	v_max_f32_e32 v67, 0, v73
	v_max_f32_e32 v69, 0, v69
	v_pk_mul_f32 v[70:71], v[70:71], v[70:71]
	v_pk_mul_f32 v[72:73], v[66:67], v[66:67]
	v_pk_mul_f32 v[76:77], v[68:69], v[68:69]
	v_cvt_pk_bf16_f32 v66, v70, v71
	v_cvt_pk_bf16_f32 v67, v72, v73
	v_cvt_pk_bf16_f32 v68, v74, v75
	v_cvt_pk_bf16_f32 v69, v76, v77
	v_max_f32_e32 v58, 0, v58
	v_max_f32_e32 v59, 0, v59
	flat_store_dwordx4 v[82:83], v[66:69] offset:256
	s_nop 1
	v_pk_mul_f32 v[68:69], v[58:59], v[58:59]
	v_max_f32_e32 v62, 0, v62
	v_max_f32_e32 v63, 0, v63
	v_max_f32_e32 v60, 0, v60
	v_pk_mul_f32 v[62:63], v[62:63], v[62:63]
	v_max_f32_e32 v58, 0, v64
	v_max_f32_e32 v59, 0, v65
	v_max_f32_e32 v61, 0, v61
	s_mov_b32 s15, 0x100000
	v_pk_mul_f32 v[64:65], v[58:59], v[58:59]
	v_pk_mul_f32 v[70:71], v[60:61], v[60:61]
	v_cvt_pk_bf16_f32 v58, v62, v63
	v_add_co_u32_e32 v62, vcc, s15, v136
	v_cvt_pk_bf16_f32 v59, v64, v65
	v_cvt_pk_bf16_f32 v60, v68, v69
	v_cvt_pk_bf16_f32 v61, v70, v71
	v_addc_co_u32_e32 v63, vcc, 0, v137, vcc
	v_max_f32_e32 v50, 0, v50
	v_max_f32_e32 v51, 0, v51
	flat_store_dwordx4 v[62:63], v[58:61]
	s_nop 1
	v_pk_mul_f32 v[58:59], v[50:51], v[50:51]
	v_max_f32_e32 v52, 0, v52
	v_max_f32_e32 v54, 0, v54
	v_max_f32_e32 v55, 0, v55
	v_max_f32_e32 v50, 0, v56
	v_max_f32_e32 v51, 0, v57
	v_max_f32_e32 v53, 0, v53
	s_mov_b64 s[24:25], 0x100000
	v_pk_mul_f32 v[54:55], v[54:55], v[54:55]
	v_pk_mul_f32 v[56:57], v[50:51], v[50:51]
	v_pk_mul_f32 v[60:61], v[52:53], v[52:53]
	v_lshl_add_u64 v[66:67], v[136:137], 0, s[24:25]
	v_cvt_pk_bf16_f32 v50, v54, v55
	v_cvt_pk_bf16_f32 v51, v56, v57
	v_cvt_pk_bf16_f32 v52, v58, v59
	v_cvt_pk_bf16_f32 v53, v60, v61
	v_max_f32_e32 v42, 0, v42
	v_max_f32_e32 v43, 0, v43
	flat_store_dwordx4 v[66:67], v[50:53] offset:256
	s_nop 1
	v_pk_mul_f32 v[52:53], v[42:43], v[42:43]
	v_max_f32_e32 v46, 0, v46
	v_max_f32_e32 v47, 0, v47
	v_max_f32_e32 v44, 0, v44
	v_pk_mul_f32 v[46:47], v[46:47], v[46:47]
	v_max_f32_e32 v42, 0, v48
	v_max_f32_e32 v43, 0, v49
	v_max_f32_e32 v45, 0, v45
	s_mov_b32 s15, 0x120000
	v_pk_mul_f32 v[48:49], v[42:43], v[42:43]
	v_pk_mul_f32 v[54:55], v[44:45], v[44:45]
	v_cvt_pk_bf16_f32 v42, v46, v47
	v_add_co_u32_e32 v46, vcc, s15, v136
	v_cvt_pk_bf16_f32 v43, v48, v49
	v_cvt_pk_bf16_f32 v44, v52, v53
	v_cvt_pk_bf16_f32 v45, v54, v55
	v_addc_co_u32_e32 v47, vcc, 0, v137, vcc
	v_max_f32_e32 v34, 0, v34
	v_max_f32_e32 v35, 0, v35
	flat_store_dwordx4 v[46:47], v[42:45]
	s_nop 1
	v_pk_mul_f32 v[42:43], v[34:35], v[34:35]
	v_max_f32_e32 v36, 0, v36
	v_max_f32_e32 v38, 0, v38
	v_max_f32_e32 v39, 0, v39
	v_max_f32_e32 v34, 0, v40
	v_max_f32_e32 v35, 0, v41
	v_max_f32_e32 v37, 0, v37
	s_mov_b64 s[24:25], 0x120000
	v_pk_mul_f32 v[38:39], v[38:39], v[38:39]
	v_pk_mul_f32 v[40:41], v[34:35], v[34:35]
	v_pk_mul_f32 v[44:45], v[36:37], v[36:37]
	v_lshl_add_u64 v[50:51], v[136:137], 0, s[24:25]
	v_cvt_pk_bf16_f32 v34, v38, v39
	v_cvt_pk_bf16_f32 v35, v40, v41
	v_cvt_pk_bf16_f32 v36, v42, v43
	v_cvt_pk_bf16_f32 v37, v44, v45
	v_max_f32_e32 v26, 0, v26
	v_max_f32_e32 v27, 0, v27
	flat_store_dwordx4 v[50:51], v[34:37] offset:256
	s_nop 1
	v_pk_mul_f32 v[36:37], v[26:27], v[26:27]
	v_max_f32_e32 v30, 0, v30
	v_max_f32_e32 v31, 0, v31
	v_max_f32_e32 v28, 0, v28
	v_pk_mul_f32 v[30:31], v[30:31], v[30:31]
	v_max_f32_e32 v26, 0, v32
	v_max_f32_e32 v27, 0, v33
	v_max_f32_e32 v29, 0, v29
	s_mov_b32 s15, 0x140000
	v_pk_mul_f32 v[32:33], v[26:27], v[26:27]
	v_pk_mul_f32 v[38:39], v[28:29], v[28:29]
	v_cvt_pk_bf16_f32 v26, v30, v31
	v_add_co_u32_e32 v30, vcc, s15, v136
	v_cvt_pk_bf16_f32 v27, v32, v33
	v_cvt_pk_bf16_f32 v28, v36, v37
	v_cvt_pk_bf16_f32 v29, v38, v39
	v_addc_co_u32_e32 v31, vcc, 0, v137, vcc
	v_max_f32_e32 v18, 0, v18
	v_max_f32_e32 v19, 0, v19
	flat_store_dwordx4 v[30:31], v[26:29]
	s_nop 1
	v_pk_mul_f32 v[26:27], v[18:19], v[18:19]
	v_max_f32_e32 v20, 0, v20
	v_max_f32_e32 v22, 0, v22
	v_max_f32_e32 v23, 0, v23
	v_max_f32_e32 v18, 0, v24
	v_max_f32_e32 v19, 0, v25
	v_max_f32_e32 v21, 0, v21
	s_mov_b64 s[24:25], 0x140000
	v_pk_mul_f32 v[22:23], v[22:23], v[22:23]
	v_pk_mul_f32 v[24:25], v[18:19], v[18:19]
	v_pk_mul_f32 v[28:29], v[20:21], v[20:21]
	v_lshl_add_u64 v[34:35], v[136:137], 0, s[24:25]
	v_cvt_pk_bf16_f32 v18, v22, v23
	v_cvt_pk_bf16_f32 v19, v24, v25
	v_cvt_pk_bf16_f32 v20, v26, v27
	v_cvt_pk_bf16_f32 v21, v28, v29
	v_max_f32_e32 v10, 0, v10
	v_max_f32_e32 v11, 0, v11
	flat_store_dwordx4 v[34:35], v[18:21] offset:256
	s_nop 1
	v_pk_mul_f32 v[20:21], v[10:11], v[10:11]
	v_max_f32_e32 v14, 0, v14
	v_max_f32_e32 v15, 0, v15
	v_max_f32_e32 v12, 0, v12
	v_pk_mul_f32 v[14:15], v[14:15], v[14:15]
	v_max_f32_e32 v10, 0, v16
	v_max_f32_e32 v11, 0, v17
	v_max_f32_e32 v13, 0, v13
	s_mov_b32 s15, 0x160000
	v_pk_mul_f32 v[16:17], v[10:11], v[10:11]
	v_pk_mul_f32 v[22:23], v[12:13], v[12:13]
	v_cvt_pk_bf16_f32 v10, v14, v15
	v_add_co_u32_e32 v14, vcc, s15, v136
	v_cvt_pk_bf16_f32 v11, v16, v17
	v_cvt_pk_bf16_f32 v12, v20, v21
	v_cvt_pk_bf16_f32 v13, v22, v23
	v_addc_co_u32_e32 v15, vcc, 0, v137, vcc
	v_max_f32_e32 v2, 0, v2
	v_max_f32_e32 v3, 0, v3
	flat_store_dwordx4 v[14:15], v[10:13]
	s_nop 1
	v_pk_mul_f32 v[10:11], v[2:3], v[2:3]
	v_max_f32_e32 v4, 0, v4
	v_max_f32_e32 v6, 0, v6
	v_max_f32_e32 v7, 0, v7
	v_max_f32_e32 v2, 0, v8
	v_max_f32_e32 v3, 0, v9
	v_max_f32_e32 v5, 0, v5
	s_mov_b64 s[24:25], 0x160000
	v_pk_mul_f32 v[6:7], v[6:7], v[6:7]
	v_pk_mul_f32 v[8:9], v[2:3], v[2:3]
	v_pk_mul_f32 v[12:13], v[4:5], v[4:5]
	v_lshl_add_u64 v[18:19], v[136:137], 0, s[24:25]
	v_cvt_pk_bf16_f32 v2, v6, v7
	v_cvt_pk_bf16_f32 v3, v8, v9
	v_cvt_pk_bf16_f32 v4, v10, v11
	v_cvt_pk_bf16_f32 v5, v12, v13
	s_andn2_b64 vcc, exec, s[0:1]
	s_mov_b64 s[0:1], -1
	flat_store_dwordx4 v[18:19], v[2:5] offset:256
	s_cbranch_vccnz .LBB0_1102
	s_andn2_b64 vcc, exec, s[10:11]
	s_cbranch_vccnz .LBB0_1101
	s_barrier
	s_branch .LBB0_1101
